# stack of all exact edits: packed-op split in every phase, ballot trim in the flash loops, all 9 GEMM tails LDS-staged
# speedup vs baseline: 1.0009x; 1.0009x over previous
; DI unsigned cvt_pk(float lo, float hi) { f32x2 v = {lo, hi}; bf16x2v b = __builtin_convertvector(v, bf16x2v); return __builtin_bit_cast(unsigned, b); }
; DI void ph_fb(const Params& p) {
;     ...
;     for (int m = gw; m < MT; m += nw) {
;         const int b_ = m / LT, pos_ = m - b_ * LT;
;         const float* hrow = pos_ < 16 ? p.meta + (size_t)pos_ * 1024 : p.x + ((size_t)b_ * 8192 + (pos_ - 16)) * 1024;
;         f32x4 hv[4];
; #pragma unroll
;         for (int i = 0; i < 4; ++i) hv[i] = *(const f32x4*)(hrow + 256 * i + 4 * lane);
; #pragma unroll
;         for (int i = 0; i < 4; ++i) {
;             *(f32x4*)(H + (size_t)m * 1024 + 256 * i + 4 * lane) = hv[i];
;             u32x2 wv; wv[0] = cvt_pk(hv[i][0], hv[i][1]); wv[1] = cvt_pk(hv[i][2], hv[i][3]);
;             *(u32x2*)(HB + (size_t)m * 1024 + 256 * i + 4 * lane) = wv;
;         }
;         float a[8];
; #pragma unroll
;         for (int j = 0; j < 8; ++j) a[j] = 0.f;
; #pragma unroll
;         for (int i = 0; i < 4; ++i)
; #pragma unroll
;             for (int e = 0; e < 4; ++e) {
;                 const float x = hv[i][e];
;                 a[0] += x * w0[i][e][0]; a[1] += x * w0[i][e][1]; a[2] += x * w0[i][e][2]; a[3] += x * w0[i][e][3];
;                 a[4] += x * w1[i][e][0]; a[5] += x * w1[i][e][1]; a[6] += x * w1[i][e][2]; a[7] += x * w1[i][e][3];
;             }
;         const bool b5 = (lane & 32) != 0, b4 = (lane & 16) != 0, b3 = (lane & 8) != 0;
;         float c4[4];
; #pragma unroll
;         for (int j = 0; j < 4; ++j) { const float send = b5 ? a[j] : a[j + 4]; const float keep = b5 ? a[j + 4] : a[j]; c4[j] = keep + __shfl_xor(send, 32); }
.LBB0_71:
	s_waitcnt vmcnt(8)
	v_mul_hi_i32 v128, v140, s3
	s_waitcnt lgkmcnt(0)
	v_lshrrev_b32_e32 v129, 31, v128
	v_ashrrev_i32_e32 v128, 12, v128
	v_add_u32_e32 v152, v128, v129
	v_mad_i32_i24 v150, v152, s20, v140
	v_cmp_lt_i32_e32 vcc, 15, v150
	v_mov_b64_e32 v[128:129], s[38:39]
	s_and_saveexec_b64 s[18:19], vcc
	s_xor_b64 s[18:19], exec, s[18:19]
	v_ashrrev_i32_e32 v153, 31, v152
	v_lshlrev_b64 v[128:129], 25, v[152:153]
	v_add_u32_e32 v130, -16, v150
	v_mov_b32_e32 v131, v143
	v_lshl_add_u64 v[128:129], s[36:37], 0, v[128:129]
	s_andn2_saveexec_b64 s[18:19], s[18:19]
	v_ashrrev_i32_e32 v151, 31, v150
	v_mov_b64_e32 v[130:131], v[150:151]
	s_or_b64 exec, exec, s[18:19]
	v_lshlrev_b64 v[130:131], 12, v[130:131]
	v_lshl_add_u64 v[128:129], v[128:129], 0, v[130:131]
	v_lshl_add_u64 v[154:155], v[128:129], 0, v[142:143]
	v_mov_b32_e32 v136, v224
	v_mov_b32_e32 v137, v225
	v_mov_b32_e32 v138, v226
	v_mov_b32_e32 v139, v227
	v_mov_b32_e32 v128, v228
	v_mov_b32_e32 v129, v229
	v_mov_b32_e32 v130, v230
	v_mov_b32_e32 v131, v231
	v_mov_b32_e32 v132, v232
	v_mov_b32_e32 v133, v233
	v_mov_b32_e32 v134, v234
	v_mov_b32_e32 v135, v235
	v_mov_b32_e32 v168, v236
	v_mov_b32_e32 v169, v237
	v_mov_b32_e32 v170, v238
	v_mov_b32_e32 v171, v239
	v_add_u32_e32 v212, s34, v140
	v_min_i32_e32 v212, s35, v212
	v_mul_hi_i32 v213, v212, s3
	v_lshrrev_b32_e32 v220, 31, v213
	v_ashrrev_i32_e32 v213, 12, v213
	v_add_u32_e32 v216, v213, v220
	v_mad_i32_i24 v218, v216, s20, v212
	v_cmp_lt_i32_e32 vcc, 15, v218
	v_mov_b64_e32 v[214:215], s[38:39]
	s_and_saveexec_b64 s[88:89], vcc
	s_xor_b64 s[88:89], exec, s[88:89]
	v_ashrrev_i32_e32 v217, 31, v216
	v_lshlrev_b64 v[214:215], 25, v[216:217]
	v_add_u32_e32 v220, -16, v218
	v_mov_b32_e32 v221, v143
	v_lshl_add_u64 v[214:215], s[36:37], 0, v[214:215]
	s_andn2_saveexec_b64 s[88:89], s[88:89]
	v_ashrrev_i32_e32 v219, 31, v218
	v_mov_b64_e32 v[220:221], v[218:219]
	s_or_b64 exec, exec, s[88:89]
	v_lshlrev_b64 v[220:221], 12, v[220:221]
	v_lshl_add_u64 v[214:215], v[214:215], 0, v[220:221]
	v_lshl_add_u64 v[222:223], v[214:215], 0, v[142:143]
	global_load_dwordx4 v[224:227], v[222:223], off
	global_load_dwordx4 v[228:231], v[222:223], off offset:1024
	global_load_dwordx4 v[232:235], v[222:223], off offset:2048
	global_load_dwordx4 v[236:239], v[222:223], off offset:3072
	v_lshl_add_u64 v[156:157], s[56:57], 0, v[144:145]
	v_add_co_u32_e32 v156, vcc, 0x3800000, v156
	v_lshl_add_u64 v[172:173], s[56:57], 0, v[146:147]
	s_nop 0
	v_addc_co_u32_e32 v157, vcc, 0, v157, vcc
	v_fma_f32 v149, v120, v136, 0
	v_fma_f32 v174, v124, v136, 0
	v_fmac_f32_e32 v149, v112, v137
	v_fmac_f32_e32 v174, v116, v137
	v_fmac_f32_e32 v149, v104, v138
	v_fmac_f32_e32 v174, v108, v138
	v_fmac_f32_e32 v149, v96, v139
	v_fmac_f32_e32 v174, v100, v139
	v_fmac_f32_e32 v149, v88, v128
	v_fmac_f32_e32 v174, v92, v128
	v_fmac_f32_e32 v149, v80, v129
	v_fmac_f32_e32 v174, v84, v129
	v_fma_f32 v151, v121, v136, 0
	v_fma_f32 v175, v125, v136, 0
	v_fmac_f32_e32 v149, v72, v130
	v_fmac_f32_e32 v174, v76, v130
	v_fma_f32 v153, v122, v136, 0
	v_fma_f32 v176, v126, v136, 0
	v_fmac_f32_e32 v151, v113, v137
	v_fmac_f32_e32 v175, v117, v137
	v_fmac_f32_e32 v149, v64, v131
	v_fmac_f32_e32 v174, v68, v131
	global_store_dwordx4 v[156:157], v[136:139], off
	v_cvt_pk_bf16_f32 v154, v136, v137
	v_fma_f32 v167, v123, v136, 0
	v_fma_f32 v136, v127, v136, 0
	v_fmac_f32_e32 v153, v114, v137
	v_fmac_f32_e32 v176, v118, v137
	v_fmac_f32_e32 v151, v105, v138
	v_fmac_f32_e32 v175, v109, v138
	v_fmac_f32_e32 v149, v56, v132
	v_fmac_f32_e32 v174, v60, v132
	v_fmac_f32_e32 v167, v115, v137
	v_fmac_f32_e32 v136, v119, v137
	v_fmac_f32_e32 v153, v106, v138
	v_fmac_f32_e32 v176, v110, v138
	v_fmac_f32_e32 v151, v97, v139
	v_fmac_f32_e32 v175, v101, v139
	v_fmac_f32_e32 v149, v48, v133
	v_fmac_f32_e32 v174, v52, v133
	v_fmac_f32_e32 v167, v107, v138
	v_fmac_f32_e32 v136, v111, v138
	v_fmac_f32_e32 v153, v98, v139
	v_fmac_f32_e32 v176, v102, v139
	v_fmac_f32_e32 v151, v89, v128
	v_fmac_f32_e32 v175, v93, v128
	v_fmac_f32_e32 v149, v40, v134
	v_fmac_f32_e32 v174, v44, v134
	v_fmac_f32_e32 v167, v99, v139
	v_fmac_f32_e32 v136, v103, v139
	v_fmac_f32_e32 v153, v90, v128
	v_fmac_f32_e32 v176, v94, v128
	v_fmac_f32_e32 v151, v81, v129
	v_fmac_f32_e32 v175, v85, v129
	v_fmac_f32_e32 v149, v32, v135
	v_fmac_f32_e32 v174, v36, v135
	v_fmac_f32_e32 v167, v91, v128
	v_fmac_f32_e32 v136, v95, v128
	v_fmac_f32_e32 v153, v82, v129
	v_fmac_f32_e32 v176, v86, v129
	v_fmac_f32_e32 v151, v73, v130
	v_fmac_f32_e32 v175, v77, v130
	v_fmac_f32_e32 v149, v24, v168
	v_fmac_f32_e32 v174, v28, v168
	v_fmac_f32_e32 v167, v83, v129
	v_fmac_f32_e32 v136, v87, v129
	v_fmac_f32_e32 v153, v74, v130
	v_fmac_f32_e32 v176, v78, v130
	v_fmac_f32_e32 v151, v65, v131
	v_fmac_f32_e32 v175, v69, v131
	v_fmac_f32_e32 v149, v16, v169
	v_fmac_f32_e32 v174, v20, v169
	v_fmac_f32_e32 v167, v75, v130
	v_fmac_f32_e32 v136, v79, v130
	v_fmac_f32_e32 v153, v66, v131
	v_fmac_f32_e32 v176, v70, v131
	v_fmac_f32_e32 v151, v57, v132
	v_fmac_f32_e32 v175, v61, v132
	v_fmac_f32_e32 v149, v8, v170
	v_fmac_f32_e32 v174, v12, v170
	v_fmac_f32_e32 v167, v67, v131
	v_fmac_f32_e32 v136, v71, v131
	v_fmac_f32_e32 v149, v0, v171
	v_fmac_f32_e32 v174, v4, v171
	v_fmac_f32_e32 v151, v49, v133
	v_fmac_f32_e32 v175, v53, v133
	v_fmac_f32_e32 v153, v58, v132
	v_fmac_f32_e32 v176, v62, v132
	v_cndmask_b32_e64 v137, v149, v174, s[0:1]
	v_fmac_f32_e32 v151, v41, v134
	v_fmac_f32_e32 v175, v45, v134
	v_fmac_f32_e32 v153, v50, v133
	v_fmac_f32_e32 v176, v54, v133
	v_fmac_f32_e32 v167, v59, v132
	v_fmac_f32_e32 v136, v63, v132
	ds_bpermute_b32 v137, v141, v137
	v_fmac_f32_e32 v151, v33, v135
	v_fmac_f32_e32 v175, v37, v135
	v_fmac_f32_e32 v153, v42, v134
	v_fmac_f32_e32 v176, v46, v134
	v_fmac_f32_e32 v167, v51, v133
	v_fmac_f32_e32 v136, v55, v133
	v_fmac_f32_e32 v151, v25, v168
	v_fmac_f32_e32 v175, v29, v168
	v_fmac_f32_e32 v153, v34, v135
	v_fmac_f32_e32 v176, v38, v135
	v_fmac_f32_e32 v167, v43, v134
	v_fmac_f32_e32 v136, v47, v134
	v_fmac_f32_e32 v151, v17, v169
	v_fmac_f32_e32 v175, v21, v169
	v_fmac_f32_e32 v153, v26, v168
	v_fmac_f32_e32 v176, v30, v168
	v_fmac_f32_e32 v167, v35, v135
	v_fmac_f32_e32 v136, v39, v135
	v_fmac_f32_e32 v151, v9, v170
	v_fmac_f32_e32 v175, v13, v170
	v_fmac_f32_e32 v153, v18, v169
	v_fmac_f32_e32 v176, v22, v169
	v_fmac_f32_e32 v167, v27, v168
	v_fmac_f32_e32 v136, v31, v168
	v_cvt_pk_bf16_f32 v155, v138, v139
	v_cndmask_b32_e64 v138, v174, v149, s[0:1]
	v_fmac_f32_e32 v151, v1, v171
	v_fmac_f32_e32 v175, v5, v171
	v_fmac_f32_e32 v153, v10, v170
	v_fmac_f32_e32 v176, v14, v170
	v_fmac_f32_e32 v167, v19, v169
	v_fmac_f32_e32 v136, v23, v169
	s_waitcnt lgkmcnt(0)
; DI void ph_fb(const Params& p) {
;     ...
;         const bool b5 = (lane & 32) != 0, b4 = (lane & 16) != 0, b3 = (lane & 8) != 0;
;         float c4[4];
; #pragma unroll
;         for (int j = 0; j < 4; ++j) { const float send = b5 ? a[j] : a[j + 4]; const float keep = b5 ? a[j + 4] : a[j]; c4[j] = keep + __shfl_xor(send, 32); }
;         float c2[2];
; #pragma unroll
;         for (int j = 0; j < 2; ++j) { const float send = b4 ? c4[j] : c4[j + 2]; const float keep = b4 ? c4[j + 2] : c4[j]; c2[j] = keep + __shfl_xor(send, 16); }
;         float v;
;         { const float send = b3 ? c2[0] : c2[1]; const float keep = b3 ? c2[1] : c2[0]; v = keep + __shfl_xor(send, 8); }
;         v += __shfl_xor(v, 4); v += __shfl_xor(v, 2); v += __shfl_xor(v, 1);
;         if ((lane & 7) == 0) {
	v_add_f32_e32 v137, v138, v137
	v_cndmask_b32_e64 v138, v151, v175, s[0:1]
	v_fmac_f32_e32 v153, v2, v171
	v_fmac_f32_e32 v176, v6, v171
	v_fmac_f32_e32 v167, v11, v170
	v_fmac_f32_e32 v136, v15, v170
	ds_bpermute_b32 v138, v141, v138
	v_cndmask_b32_e64 v149, v153, v176, s[0:1]
	v_fmac_f32_e32 v167, v3, v171
	v_fmac_f32_e32 v136, v7, v171
	v_cndmask_b32_e64 v139, v175, v151, s[0:1]
	ds_bpermute_b32 v149, v141, v149
	v_cndmask_b32_e64 v151, v167, v136, s[0:1]
	ds_bpermute_b32 v151, v141, v151
	s_waitcnt lgkmcnt(2)
	v_add_f32_e32 v138, v139, v138
	v_cndmask_b32_e64 v139, v176, v153, s[0:1]
	s_waitcnt lgkmcnt(1)
	v_add_f32_e32 v139, v139, v149
	v_cndmask_b32_e64 v136, v136, v167, s[0:1]
	s_waitcnt lgkmcnt(0)
	v_add_f32_e32 v149, v136, v151
	v_cndmask_b32_e64 v136, v137, v139, s[4:5]
	ds_bpermute_b32 v151, v160, v136
	v_cndmask_b32_e64 v136, v138, v149, s[4:5]
	ds_bpermute_b32 v153, v160, v136
	v_cndmask_b32_e64 v137, v139, v137, s[4:5]
	v_add_co_u32_e32 v136, vcc, s21, v172
	s_waitcnt lgkmcnt(1)
	v_add_f32_e32 v139, v137, v151
	v_cndmask_b32_e64 v137, v149, v138, s[4:5]
	s_waitcnt lgkmcnt(0)
	v_add_f32_e32 v138, v137, v153
	v_cndmask_b32_e64 v137, v139, v138, s[6:7]
	ds_bpermute_b32 v149, v161, v137
	v_cndmask_b32_e64 v138, v138, v139, s[6:7]
	v_addc_co_u32_e32 v137, vcc, 0, v173, vcc
	global_store_dwordx2 v[136:137], v[154:155], off
	s_waitcnt lgkmcnt(0)
	v_add_f32_e32 v149, v138, v149
	ds_bpermute_b32 v151, v162, v149
	v_cvt_pk_bf16_f32 v138, v128, v129
	v_cvt_pk_bf16_f32 v139, v130, v131
	global_store_dwordx4 v[156:157], v[128:131], off offset:1024
	global_store_dwordx2 v[136:137], v[138:139], off offset:512
	global_store_dwordx4 v[156:157], v[132:135], off offset:2048
	s_waitcnt lgkmcnt(0)
	v_add_f32_e32 v130, v149, v151
	ds_bpermute_b32 v131, v163, v130
	v_cvt_pk_bf16_f32 v128, v132, v133
	v_cvt_pk_bf16_f32 v129, v134, v135
	global_store_dwordx2 v[136:137], v[128:129], off offset:1024
	global_store_dwordx4 v[156:157], v[168:171], off offset:3072
	s_waitcnt lgkmcnt(0)
	v_add_f32_e32 v128, v130, v131
	ds_bpermute_b32 v129, v164, v128
	v_cvt_pk_bf16_f32 v130, v168, v169
	v_cvt_pk_bf16_f32 v131, v170, v171
	global_store_dwordx2 v[136:137], v[130:131], off offset:1536
	s_and_saveexec_b64 s[18:19], s[8:9]
	s_cbranch_execz .LBB0_70
; DI void ph_fb(const Params& p) {
;     ...
;         if ((lane & 7) == 0) {
;             const float xx = v + fbias;
;             const float ls = fminf(xx, 0.f) - log1pf(expf(-fabsf(xx)));
;             const int b = m / LT, pos = m - b * LT;
;             LF[(size_t)(b * 8 + j8) * LP + pos] = ls;
;         }
	s_waitcnt lgkmcnt(0)
	v_add_f32_e32 v128, v128, v129
	v_add_f32_e32 v128, v159, v128
	v_mul_f32_e64 v129, |v128|, s22
	v_fma_f32 v130, |v128|, s22, -v129
	v_rndne_f32_e32 v131, v129
	v_fma_f32 v130, |v128|, s23, v130
	v_sub_f32_e32 v129, v129, v131
	v_add_f32_e32 v129, v129, v130
	v_exp_f32_e32 v129, v129
	v_cvt_i32_f32_e32 v130, v131
	v_cmp_ngt_f32_e64 vcc, |v128|, s24
	v_min_f32_e32 v151, 0, v128
	v_ldexp_f32 v129, v129, v130
	v_cndmask_b32_e32 v129, 0, v129, vcc
	v_cmp_nlt_f32_e64 vcc, |v128|, s25
	s_nop 1
	v_cndmask_b32_e32 v153, v166, v129, vcc
	v_add_f32_e32 v130, 1.0, v153
	v_add_f32_e32 v128, -1.0, v130
	v_sub_f32_e32 v129, v128, v130
	v_add_f32_e32 v129, 1.0, v129
	v_sub_f32_e32 v128, v153, v128
	v_add_f32_e32 v131, v128, v129
	v_frexp_mant_f32_e32 v132, v130
	v_cvt_f64_f32_e32 v[128:129], v130
	v_frexp_exp_i32_f64_e32 v128, v[128:129]
	v_cmp_gt_f32_e32 vcc, s27, v132
	s_nop 1
	v_subbrev_co_u32_e32 v136, vcc, 0, v128, vcc
	v_sub_u32_e32 v128, 0, v136
	v_ldexp_f32 v129, v130, v128
	v_add_f32_e32 v130, -1.0, v129
	v_add_f32_e32 v132, 1.0, v129
	v_ldexp_f32 v128, v131, v128
	v_add_f32_e32 v131, 1.0, v130
	v_add_f32_e32 v133, -1.0, v132
	v_sub_f32_e32 v131, v129, v131
	v_sub_f32_e32 v129, v129, v133
	v_add_f32_e32 v131, v128, v131
	v_add_f32_e32 v128, v128, v129
	v_add_f32_e32 v137, v132, v128
	v_rcp_f32_e32 v139, v137
	v_sub_f32_e32 v129, v132, v137
	v_add_f32_e32 v138, v128, v129
	v_add_f32_e32 v129, v130, v131
	v_mul_f32_e32 v154, v129, v139
	v_sub_f32_e32 v128, v130, v129
	v_mul_f32_e32 v130, v137, v154
	v_fma_f32 v132, v154, v137, -v130
	v_fmac_f32_e32 v132, v154, v138
	v_add_f32_e32 v149, v131, v128
	v_add_f32_e32 v128, v130, v132
	v_sub_f32_e32 v131, v129, v128
	v_add_f32_e64 v134, v128, -v130
	v_add_f32_e64 v135, v129, -v131
	v_mov_b32_e32 v133, v128
	v_add_f32_e64 v128, v134, -v132
	v_add_f32_e64 v129, v135, -v133
	v_cmp_neq_f32_e32 vcc, s26, v153
	v_add_f32_e32 v129, v149, v129
	v_add_f32_e32 v128, v128, v129
	v_add_f32_e32 v129, v131, v128
	v_mul_f32_e32 v149, v139, v129
	v_mul_f32_e32 v130, v137, v149
	v_fma_f32 v132, v149, v137, -v130
	v_fmac_f32_e32 v132, v149, v138
	v_sub_f32_e32 v131, v131, v129
	v_add_f32_e32 v137, v128, v131
	v_add_f32_e32 v128, v130, v132
	v_sub_f32_e32 v131, v129, v128
	v_add_f32_e64 v134, v128, -v130
	v_add_f32_e64 v135, v129, -v131
	v_mov_b32_e32 v133, v128
	v_add_f32_e64 v128, v134, -v132
	v_add_f32_e64 v129, v135, -v133
	s_nop 0
	v_add_f32_e32 v129, v137, v129
	v_add_f32_e32 v128, v128, v129
	v_add_f32_e32 v129, v154, v149
	v_add_f32_e32 v128, v131, v128
	v_sub_f32_e32 v130, v129, v154
	v_mul_f32_e32 v128, v139, v128
	v_sub_f32_e32 v130, v149, v130
	v_add_f32_e32 v130, v130, v128
	v_add_f32_e32 v132, v129, v130
	v_mul_f32_e32 v133, v132, v132
	v_fmamk_f32 v128, v133, 0x3e9b6dac, v165
	v_fmaak_f32 v149, v133, v128, 0x3f2aaada
	v_cvt_f32_i32_e32 v128, v136
	v_sub_f32_e32 v129, v132, v129
	v_sub_f32_e32 v129, v130, v129
	v_ldexp_f32 v134, v129, 1
	v_mul_f32_e32 v129, v132, v133
	v_ldexp_f32 v131, v132, 1
	v_mul_f32_e64 v132, v128, v148
	v_mul_f32_e64 v133, v129, v149
	s_nop 0
	v_fma_f32 v130, v128, s28, -v132
	v_fmac_f32_e32 v130, 0xb102e308, v128
	v_add_f32_e64 v128, v132, v130
	v_add_f32_e64 v129, v133, v131
	s_nop 0
	v_sub_f32_e32 v131, v129, v131
	v_sub_f32_e32 v131, v133, v131
	v_add_f32_e32 v135, v134, v131
	v_mov_b32_e32 v134, v132
	v_add_f32_e64 v132, v128, -v132
	v_add_f32_e64 v133, v129, -v133
	v_add_f32_e64 v136, v128, v134
	v_add_f32_e64 v137, v129, v135
	v_mov_b32_e32 v131, v128
	v_mov_b32_e32 v133, v137
	v_add_f32_e64 v138, v130, -v132
	v_add_f32_e64 v139, v131, -v133
	v_add_f32_e64 v130, v130, v132
	v_add_f32_e64 v131, v131, v133
	v_mov_b32_e32 v134, v135
	v_add_f32_e64 v132, v131, -v128
	v_add_f32_e64 v133, v130, -v129
	v_add_f32_e64 v154, v136, -v132
	v_add_f32_e64 v155, v137, -v132
	v_mov_b32_e32 v136, v137
	v_mov_b32_e32 v137, v131
	v_pk_mov_b32 v[132:133], v[128:129], v[132:133] op_sel:[1,0]
	v_mov_b32_e32 v135, v128
	v_add_f32_e64 v132, v136, -v132
	v_add_f32_e64 v133, v137, -v133
	v_mov_b32_e32 v154, v138
	v_add_f32_e64 v128, v134, -v132
	v_add_f32_e64 v129, v135, -v133
	v_mov_b32_e32 v139, v131
	v_add_f32_e64 v132, v154, v128
	v_add_f32_e64 v133, v155, v129
	s_nop 0
	v_add_f32_e64 v134, v132, v133
	v_add_f32_e64 v135, v133, v132
	s_nop 0
	v_pk_add_f32 v[130:131], v[130:131], v[134:135] op_sel:[1,0] op_sel_hi:[0,1]
	v_mov_b32_e32 v133, v130
	v_add_f32_e64 v136, v132, -v138
	v_add_f32_e64 v137, v133, -v139
	v_mov_b32_e32 v129, v134
	v_sub_f32_e32 v131, v132, v136
	v_add_f32_e64 v128, v128, -v136
	v_add_f32_e64 v129, v129, -v137
	v_sub_f32_e32 v131, v138, v131
	v_add_f32_e32 v128, v128, v131
	v_add_f32_e32 v128, v128, v129
	v_add_f32_e32 v128, v130, v128
	v_cndmask_b32_e32 v128, v166, v128, vcc
	v_cmp_lt_f32_e64 vcc, |v153|, s29
	s_nop 1
	v_cndmask_b32_e32 v128, v128, v153, vcc
	v_sub_f32_e32 v130, v151, v128
	v_lshl_or_b32 v128, v152, 3, v158
	v_mul_hi_i32_i24_e32 v129, 0x8200, v128
	v_mul_i32_i24_e32 v128, 0x8200, v128
	v_ashrrev_i32_e32 v151, 31, v150
	v_lshl_add_u64 v[128:129], s[48:49], 0, v[128:129]
	v_lshl_add_u64 v[128:129], v[150:151], 2, v[128:129]
	global_store_dword v[128:129], v130, off
	s_branch .LBB0_70

; DI unsigned cvt_pk(float lo, float hi) { f32x2 v = {lo, hi}; bf16x2v b = __builtin_convertvector(v, bf16x2v); return __builtin_bit_cast(unsigned, b); }
; DI void ph_ln(const Params& p, int lnidx, bool last) {
;     ...
;     for (int m = gw; m < MT; m += nw) {
;         f32x4 v[4];
; #pragma unroll
;         for (int i = 0; i < 4; ++i) v[i] = nv[i];
;         const int mn = min(m + nw, MT - 1);
; #pragma unroll
;         for (int i = 0; i < 4; ++i) nv[i] = *(const f32x4*)(H + (size_t)mn * 1024 + i * 256 + lane * 4);
;         float s = 0.f;
; #pragma unroll
;         for (int i = 0; i < 4; ++i) s += (v[i][0] + v[i][1]) + (v[i][2] + v[i][3]);
;         for (int o = 32; o > 0; o >>= 1) s += __shfl_xor(s, o);
;         const float mu = s * (1.0f / 1024.0f);
;         float qv = 0.f;
; #pragma unroll
;         for (int i = 0; i < 4; ++i)
; #pragma unroll
;             for (int e = 0; e < 4; ++e) { const float d = v[i][e] - mu; qv += d * d; }
;         for (int o = 32; o > 0; o >>= 1) qv += __shfl_xor(qv, o);
;         const float rstd = __frsqrt_rn(qv * (1.0f / 1024.0f) + 1e-5f);
;         const int b = m / LT, pos = m - b * LT;
; #pragma unroll
;         for (int i = 0; i < 4; ++i) {
;             const int c = i * 256 + lane * 4;
;             f32x4 y;
; #pragma unroll
;             for (int e = 0; e < 4; ++e) y[e] = (v[i][e] - mu) * rstd * g[i][e] + bb[i][e];
;             if (last) {
;                 if (pos >= 16) *(f32x4*)(p.out + ((size_t)b * 8192 + (pos - 16)) * 1024 + c) = y;
;             } else {
;                 u32x2 wv; wv[0] = cvt_pk(y[0], y[1]); wv[1] = cvt_pk(y[2], y[3]);
;                 *(u32x2*)(HB + (size_t)m * 1024 + c) = wv;
;             }
;         }
;         if (!last && lane == 0) ((f32x2*)((unsigned char*)p.out + OFFO_STATS))[m] = (f32x2){mu, rstd};
.LBB0_858:
	v_add_f32_e64 v38, v58, v44
	v_add_f32_e64 v39, v59, v45
	v_add_f32_e64 v46, v70, v36
	v_add_f32_e64 v47, v71, v37
	v_add_f32_e32 v38, v38, v39
	v_add_f32_e64 v47, v46, v47
	v_add_f32_e64 v46, v46, v46
	v_add_f32_e32 v39, 0, v38
	s_waitcnt vmcnt(1)
	v_add_f32_e32 v49, v32, v33
	v_add_f32_e32 v51, v34, v35
	s_waitcnt vmcnt(0)
	v_mov_b32_e32 v48, v40
	v_mov_b32_e32 v50, v41
	v_mov_b32_e32 v46, v42
	v_mov_b32_e32 v38, v43
	v_add_f32_e64 v48, v48, v50
	v_add_f32_e64 v49, v49, v51
	v_add_f32_e64 v38, v46, v38
	v_add_f32_e64 v39, v47, v39
	v_add_u32_e32 v62, s34, v62
	v_add_f32_e64 v38, v48, v38
	v_add_f32_e64 v39, v49, v39
	v_mov_b32_e32 v78, v59
	v_add_f32_e32 v38, v38, v39
	ds_bpermute_b32 v39, v63, v38
	v_mov_b32_e32 v79, v45
	v_mov_b32_e32 v45, v58
	v_mov_b32_e32 v86, v71
	v_mov_b32_e32 v87, v37
	s_waitcnt lgkmcnt(0)
	v_add_f32_e32 v38, v38, v39
	ds_bpermute_b32 v39, v73, v38
	v_mov_b32_e32 v37, v70
	s_waitcnt lgkmcnt(0)
	v_add_f32_e32 v38, v38, v39
	ds_bpermute_b32 v39, v74, v38
	s_waitcnt lgkmcnt(0)
	v_add_f32_e32 v38, v38, v39
	ds_bpermute_b32 v39, v75, v38
	s_waitcnt lgkmcnt(0)
	v_add_f32_e32 v46, v38, v39
	ds_bpermute_b32 v47, v76, v46
	v_min_i32_e32 v38, 0x803f, v62
	v_ashrrev_i32_e32 v39, 31, v38
	v_lshlrev_b64 v[38:39], 12, v[38:39]
	v_lshl_add_u64 v[38:39], v[64:65], 0, v[38:39]
	s_waitcnt lgkmcnt(0)
	v_add_f32_e32 v80, v46, v47
	global_load_dwordx4 v[58:61], v[38:39], off
	global_load_dwordx4 v[54:57], v[38:39], off offset:1024
	global_load_dwordx4 v[50:53], v[38:39], off offset:2048
	global_load_dwordx4 v[46:49], v[38:39], off offset:3072
	ds_bpermute_b32 v81, v77, v80
	s_waitcnt lgkmcnt(0)
	v_add_f32_e32 v38, v80, v81
	v_mul_f32_e32 v38, 0x3a800000, v38
	v_add_f32_e64 v44, v44, -v38
	v_add_f32_e64 v45, v45, -v38
	v_add_f32_e64 v78, v78, -v38
	v_add_f32_e64 v79, v79, -v38
	v_mul_f32_e64 v84, v44, v44
	v_mul_f32_e64 v85, v45, v45
	v_add_f32_e64 v42, v42, -v38
	v_add_f32_e64 v43, v43, -v38
	v_mul_f32_e64 v82, v78, v78
	v_mul_f32_e64 v83, v79, v79
	v_add_f32_e64 v86, v86, -v38
	v_add_f32_e64 v87, v87, -v38
	v_add_f32_e64 v36, v36, -v38
	v_add_f32_e64 v37, v37, -v38
	v_add_f32_e64 v34, v34, -v38
	v_add_f32_e64 v35, v35, -v38
	v_add_f32_e64 v92, v32, -v38
	v_add_f32_e64 v93, v33, -v38
	v_add_f32_e64 v40, v40, -v38
	v_add_f32_e64 v41, v41, -v38
	v_add_f32_e32 v39, v84, v85
	v_add_f32_e32 v39, v82, v39
	v_mul_f32_e64 v70, v36, v36
	v_mul_f32_e64 v71, v37, v37
	v_add_f32_e32 v39, v83, v39
	v_add_f32_e32 v39, v70, v39
	v_mul_f32_e64 v88, v86, v86
	v_mul_f32_e64 v89, v87, v87
	v_add_f32_e32 v39, v71, v39
	v_add_f32_e32 v39, v88, v39
	v_mul_f32_e64 v32, v92, v92
	v_mul_f32_e64 v33, v93, v93
	v_add_f32_e32 v39, v89, v39
	v_add_f32_e32 v32, v32, v39
	v_mul_f32_e64 v90, v34, v34
	v_mul_f32_e64 v91, v35, v35
	v_add_f32_e32 v32, v33, v32
	v_add_f32_e32 v32, v90, v32
	v_mul_f32_e64 v94, v40, v40
	v_mul_f32_e64 v95, v41, v41
	v_add_f32_e32 v32, v91, v32
	v_add_f32_e32 v32, v94, v32
	v_mul_f32_e64 v80, v42, v42
	v_mul_f32_e64 v81, v43, v43
	v_add_f32_e32 v32, v95, v32
	v_add_f32_e32 v32, v80, v32
	v_add_f32_e32 v32, v81, v32
	ds_bpermute_b32 v33, v63, v32
	s_waitcnt lgkmcnt(0)
	v_add_f32_e32 v32, v32, v33
	ds_bpermute_b32 v33, v73, v32
	s_waitcnt lgkmcnt(0)
	v_add_f32_e32 v32, v32, v33
	ds_bpermute_b32 v33, v74, v32
	s_waitcnt lgkmcnt(0)
	v_add_f32_e32 v32, v32, v33
	ds_bpermute_b32 v33, v75, v32
	s_waitcnt lgkmcnt(0)
	v_add_f32_e32 v32, v32, v33
	ds_bpermute_b32 v33, v76, v32
	s_waitcnt lgkmcnt(0)
	v_add_f32_e32 v32, v32, v33
	ds_bpermute_b32 v33, v77, v32
	s_waitcnt lgkmcnt(0)
	v_add_f32_e32 v32, v32, v33
	v_fmamk_f32 v32, v32, 0x3a800000, v72
	v_rsq_f32_e32 v32, v32
	s_nop 0
	v_mul_f32_e64 v44, v44, v32
	v_mul_f32_e64 v45, v45, v32
	v_mul_f32_e64 v70, v78, v32
	v_mul_f32_e64 v71, v79, v32
	v_mul_f32_e64 v36, v36, v32
	v_mul_f32_e64 v37, v37, v32
	v_mul_f32_e64 v78, v86, v32
	v_mul_f32_e64 v79, v87, v32
	v_mul_f32_e64 v80, v92, v32
	v_mul_f32_e64 v81, v93, v32
	v_mul_f32_e64 v34, v34, v32
	v_mul_f32_e64 v35, v35, v32
	v_fma_f32 v44, v28, v44, v24
	v_fma_f32 v45, v29, v45, v25
	v_fma_f32 v70, v30, v70, v26
	v_fma_f32 v71, v31, v71, v27
	v_fma_f32 v36, v20, v36, v16
	v_fma_f32 v37, v21, v37, v17
	v_fma_f32 v78, v22, v78, v18
	v_fma_f32 v79, v23, v79, v19
	v_fma_f32 v80, v12, v80, v8
	v_fma_f32 v81, v13, v81, v9
	v_cvt_pk_bf16_f32 v44, v44, v45
	v_cvt_pk_bf16_f32 v45, v70, v71
	v_cvt_pk_bf16_f32 v36, v36, v37
	v_cvt_pk_bf16_f32 v37, v78, v79
	v_fma_f32 v34, v14, v34, v10
	v_fma_f32 v35, v15, v35, v11
	global_store_dwordx2 v[68:69], v[44:45], off
	global_store_dwordx2 v[68:69], v[36:37], off offset:512
	v_cvt_pk_bf16_f32 v36, v80, v81
	v_cvt_pk_bf16_f32 v37, v34, v35
	global_store_dwordx2 v[68:69], v[36:37], off offset:1024
	v_mul_f32_e64 v34, v40, v32
	v_mul_f32_e64 v35, v41, v32
	v_mul_f32_e64 v36, v42, v32
	v_mul_f32_e64 v37, v43, v32
	v_fma_f32 v34, v4, v34, v0
	v_fma_f32 v35, v5, v35, v1
	v_fma_f32 v36, v6, v36, v2
	v_fma_f32 v37, v7, v37, v3
	v_cvt_pk_bf16_f32 v34, v34, v35
	v_cvt_pk_bf16_f32 v35, v36, v37
	global_store_dwordx2 v[68:69], v[34:35], off offset:1536
	s_and_saveexec_b64 s[0:1], vcc
	s_cbranch_execz .LBB0_857
	v_mov_b32_e32 v39, v32
	global_store_dwordx2 v[66:67], v[38:39], off
	s_branch .LBB0_857

; DI unsigned cvt_pk(float lo, float hi) { f32x2 v = {lo, hi}; bf16x2v b = __builtin_convertvector(v, bf16x2v); return __builtin_bit_cast(unsigned, b); }
; DI void ph_ln(const Params& p, int lnidx, bool last) {
;     ...
;     for (int m = gw; m < MT; m += nw) {
;         f32x4 v[4];
; #pragma unroll
;         for (int i = 0; i < 4; ++i) v[i] = nv[i];
;         const int mn = min(m + nw, MT - 1);
; #pragma unroll
;         for (int i = 0; i < 4; ++i) nv[i] = *(const f32x4*)(H + (size_t)mn * 1024 + i * 256 + lane * 4);
;         float s = 0.f;
; #pragma unroll
;         for (int i = 0; i < 4; ++i) s += (v[i][0] + v[i][1]) + (v[i][2] + v[i][3]);
;         for (int o = 32; o > 0; o >>= 1) s += __shfl_xor(s, o);
;         const float mu = s * (1.0f / 1024.0f);
;         float qv = 0.f;
; #pragma unroll
;         for (int i = 0; i < 4; ++i)
; #pragma unroll
;             for (int e = 0; e < 4; ++e) { const float d = v[i][e] - mu; qv += d * d; }
;         for (int o = 32; o > 0; o >>= 1) qv += __shfl_xor(qv, o);
;         const float rstd = __frsqrt_rn(qv * (1.0f / 1024.0f) + 1e-5f);
;         const int b = m / LT, pos = m - b * LT;
; #pragma unroll
;         for (int i = 0; i < 4; ++i) {
;             const int c = i * 256 + lane * 4;
;             f32x4 y;
; #pragma unroll
;             for (int e = 0; e < 4; ++e) y[e] = (v[i][e] - mu) * rstd * g[i][e] + bb[i][e];
;             if (last) {
;                 if (pos >= 16) *(f32x4*)(p.out + ((size_t)b * 8192 + (pos - 16)) * 1024 + c) = y;
;             } else {
;                 u32x2 wv; wv[0] = cvt_pk(y[0], y[1]); wv[1] = cvt_pk(y[2], y[3]);
;                 *(u32x2*)(HB + (size_t)m * 1024 + c) = wv;
;             }
;         }
;         if (!last && lane == 0) ((f32x2*)((unsigned char*)p.out + OFFO_STATS))[m] = (f32x2){mu, rstd};
.LBB0_1071:
	v_add_f32_e64 v38, v58, v44
	v_add_f32_e64 v39, v59, v45
	v_add_f32_e64 v46, v70, v36
	v_add_f32_e64 v47, v71, v37
	v_add_f32_e32 v38, v38, v39
	v_add_f32_e64 v47, v46, v47
	v_add_f32_e64 v46, v46, v46
	v_add_f32_e32 v39, 0, v38
	s_waitcnt vmcnt(2)
	v_add_f32_e32 v49, v32, v33
	v_add_f32_e32 v51, v34, v35
	s_waitcnt vmcnt(1)
	v_mov_b32_e32 v48, v40
	v_mov_b32_e32 v50, v41
	v_mov_b32_e32 v46, v42
	v_mov_b32_e32 v38, v43
	v_add_f32_e64 v48, v48, v50
	v_add_f32_e64 v49, v49, v51
	v_add_f32_e64 v38, v46, v38
	v_add_f32_e64 v39, v47, v39
	v_add_u32_e32 v62, s34, v62
	v_add_f32_e64 v38, v48, v38
	v_add_f32_e64 v39, v49, v39
	v_mov_b32_e32 v78, v59
	v_add_f32_e32 v38, v38, v39
	ds_bpermute_b32 v39, v63, v38
	v_mov_b32_e32 v79, v45
	v_mov_b32_e32 v45, v58
	v_mov_b32_e32 v86, v71
	v_mov_b32_e32 v87, v37
	s_waitcnt lgkmcnt(0)
	v_add_f32_e32 v38, v38, v39
	ds_bpermute_b32 v39, v73, v38
	v_mov_b32_e32 v37, v70
	s_waitcnt lgkmcnt(0)
	v_add_f32_e32 v38, v38, v39
	ds_bpermute_b32 v39, v74, v38
	s_waitcnt lgkmcnt(0)
	v_add_f32_e32 v38, v38, v39
	ds_bpermute_b32 v39, v75, v38
	s_waitcnt lgkmcnt(0)
	v_add_f32_e32 v46, v38, v39
	ds_bpermute_b32 v47, v76, v46
	v_min_i32_e32 v38, 0x803f, v62
	v_ashrrev_i32_e32 v39, 31, v38
	v_lshlrev_b64 v[38:39], 12, v[38:39]
	v_lshl_add_u64 v[38:39], v[64:65], 0, v[38:39]
	s_waitcnt lgkmcnt(0)
	v_add_f32_e32 v80, v46, v47
	global_load_dwordx4 v[58:61], v[38:39], off
	global_load_dwordx4 v[54:57], v[38:39], off offset:1024
	global_load_dwordx4 v[50:53], v[38:39], off offset:2048
	global_load_dwordx4 v[46:49], v[38:39], off offset:3072
	ds_bpermute_b32 v81, v77, v80
	s_waitcnt lgkmcnt(0)
	v_add_f32_e32 v38, v80, v81
	v_mul_f32_e32 v38, 0x3a800000, v38
	v_add_f32_e64 v44, v44, -v38
	v_add_f32_e64 v45, v45, -v38
	v_add_f32_e64 v78, v78, -v38
	v_add_f32_e64 v79, v79, -v38
	v_mul_f32_e64 v84, v44, v44
	v_mul_f32_e64 v85, v45, v45
	v_add_f32_e64 v42, v42, -v38
	v_add_f32_e64 v43, v43, -v38
	v_mul_f32_e64 v82, v78, v78
	v_mul_f32_e64 v83, v79, v79
	v_add_f32_e64 v86, v86, -v38
	v_add_f32_e64 v87, v87, -v38
	v_add_f32_e64 v36, v36, -v38
	v_add_f32_e64 v37, v37, -v38
	v_add_f32_e64 v34, v34, -v38
	v_add_f32_e64 v35, v35, -v38
	v_add_f32_e64 v92, v32, -v38
	v_add_f32_e64 v93, v33, -v38
	v_add_f32_e64 v40, v40, -v38
	v_add_f32_e64 v41, v41, -v38
	v_add_f32_e32 v39, v84, v85
	v_add_f32_e32 v39, v82, v39
	v_mul_f32_e64 v70, v36, v36
	v_mul_f32_e64 v71, v37, v37
	v_add_f32_e32 v39, v83, v39
	v_add_f32_e32 v39, v70, v39
	v_mul_f32_e64 v88, v86, v86
	v_mul_f32_e64 v89, v87, v87
	v_add_f32_e32 v39, v71, v39
	v_add_f32_e32 v39, v88, v39
	v_mul_f32_e64 v32, v92, v92
	v_mul_f32_e64 v33, v93, v93
	v_add_f32_e32 v39, v89, v39
	v_add_f32_e32 v32, v32, v39
	v_mul_f32_e64 v90, v34, v34
	v_mul_f32_e64 v91, v35, v35
	v_add_f32_e32 v32, v33, v32
	v_add_f32_e32 v32, v90, v32
	v_mul_f32_e64 v94, v40, v40
	v_mul_f32_e64 v95, v41, v41
	v_add_f32_e32 v32, v91, v32
	v_add_f32_e32 v32, v94, v32
	v_mul_f32_e64 v80, v42, v42
	v_mul_f32_e64 v81, v43, v43
	v_add_f32_e32 v32, v95, v32
	v_add_f32_e32 v32, v80, v32
	v_add_f32_e32 v32, v81, v32
	ds_bpermute_b32 v33, v63, v32
	s_waitcnt lgkmcnt(0)
	v_add_f32_e32 v32, v32, v33
	ds_bpermute_b32 v33, v73, v32
	s_waitcnt lgkmcnt(0)
	v_add_f32_e32 v32, v32, v33
	ds_bpermute_b32 v33, v74, v32
	s_waitcnt lgkmcnt(0)
	v_add_f32_e32 v32, v32, v33
	ds_bpermute_b32 v33, v75, v32
	s_waitcnt lgkmcnt(0)
	v_add_f32_e32 v32, v32, v33
	ds_bpermute_b32 v33, v76, v32
	s_waitcnt lgkmcnt(0)
	v_add_f32_e32 v32, v32, v33
	ds_bpermute_b32 v33, v77, v32
	s_waitcnt lgkmcnt(0)
	v_add_f32_e32 v32, v32, v33
	v_fmamk_f32 v32, v32, 0x3a800000, v72
	v_rsq_f32_e32 v32, v32
	s_nop 0
	v_mul_f32_e64 v44, v44, v32
	v_mul_f32_e64 v45, v45, v32
	v_mul_f32_e64 v70, v78, v32
	v_mul_f32_e64 v71, v79, v32
	v_mul_f32_e64 v36, v36, v32
	v_mul_f32_e64 v37, v37, v32
	v_mul_f32_e64 v78, v86, v32
	v_mul_f32_e64 v79, v87, v32
	v_mul_f32_e64 v80, v92, v32
	v_mul_f32_e64 v81, v93, v32
	v_mul_f32_e64 v34, v34, v32
	v_mul_f32_e64 v35, v35, v32
	s_waitcnt vmcnt(4)
	v_fma_f32 v44, v28, v44, v24
	v_fma_f32 v45, v29, v45, v25
	v_fma_f32 v70, v30, v70, v26
	v_fma_f32 v71, v31, v71, v27
	v_fma_f32 v36, v20, v36, v12
	v_fma_f32 v37, v21, v37, v13
	v_fma_f32 v78, v22, v78, v14
	v_fma_f32 v79, v23, v79, v15
	v_fma_f32 v80, v16, v80, v8
	v_fma_f32 v81, v17, v81, v9
	v_cvt_pk_bf16_f32 v44, v44, v45
	v_cvt_pk_bf16_f32 v45, v70, v71
	v_cvt_pk_bf16_f32 v36, v36, v37
	v_cvt_pk_bf16_f32 v37, v78, v79
	v_fma_f32 v34, v18, v34, v10
	v_fma_f32 v35, v19, v35, v11
	global_store_dwordx2 v[68:69], v[44:45], off
	global_store_dwordx2 v[68:69], v[36:37], off offset:512
	v_cvt_pk_bf16_f32 v36, v80, v81
	v_cvt_pk_bf16_f32 v37, v34, v35
	global_store_dwordx2 v[68:69], v[36:37], off offset:1024
	v_mul_f32_e64 v34, v40, v32
	v_mul_f32_e64 v35, v41, v32
	v_mul_f32_e64 v36, v42, v32
	v_mul_f32_e64 v37, v43, v32
	v_fma_f32 v34, v4, v34, v0
	v_fma_f32 v35, v5, v35, v1
	v_fma_f32 v36, v6, v36, v2
	v_fma_f32 v37, v7, v37, v3
	v_cvt_pk_bf16_f32 v34, v34, v35
	v_cvt_pk_bf16_f32 v35, v36, v37
	global_store_dwordx2 v[68:69], v[34:35], off offset:1536
	s_and_saveexec_b64 s[4:5], vcc
	s_cbranch_execz .LBB0_1070
	v_mov_b32_e32 v39, v32
	global_store_dwordx2 v[66:67], v[38:39], off
	s_branch .LBB0_1070

; DI unsigned cvt_pk(float lo, float hi) { f32x2 v = {lo, hi}; bf16x2v b = __builtin_convertvector(v, bf16x2v); return __builtin_bit_cast(unsigned, b); }
; DI void ph_ln(const Params& p, int lnidx, bool last) {
;     ...
;     for (int m = gw; m < MT; m += nw) {
;         f32x4 v[4];
; #pragma unroll
;         for (int i = 0; i < 4; ++i) v[i] = nv[i];
;         const int mn = min(m + nw, MT - 1);
; #pragma unroll
;         for (int i = 0; i < 4; ++i) nv[i] = *(const f32x4*)(H + (size_t)mn * 1024 + i * 256 + lane * 4);
;         float s = 0.f;
; #pragma unroll
;         for (int i = 0; i < 4; ++i) s += (v[i][0] + v[i][1]) + (v[i][2] + v[i][3]);
;         for (int o = 32; o > 0; o >>= 1) s += __shfl_xor(s, o);
;         const float mu = s * (1.0f / 1024.0f);
;         float qv = 0.f;
; #pragma unroll
;         for (int i = 0; i < 4; ++i)
; #pragma unroll
;             for (int e = 0; e < 4; ++e) { const float d = v[i][e] - mu; qv += d * d; }
;         for (int o = 32; o > 0; o >>= 1) qv += __shfl_xor(qv, o);
;         const float rstd = __frsqrt_rn(qv * (1.0f / 1024.0f) + 1e-5f);
;         const int b = m / LT, pos = m - b * LT;
; #pragma unroll
;         for (int i = 0; i < 4; ++i) {
;             const int c = i * 256 + lane * 4;
;             f32x4 y;
; #pragma unroll
;             for (int e = 0; e < 4; ++e) y[e] = (v[i][e] - mu) * rstd * g[i][e] + bb[i][e];
;             if (last) {
;                 if (pos >= 16) *(f32x4*)(p.out + ((size_t)b * 8192 + (pos - 16)) * 1024 + c) = y;
;             } else {
;                 u32x2 wv; wv[0] = cvt_pk(y[0], y[1]); wv[1] = cvt_pk(y[2], y[3]);
;                 *(u32x2*)(HB + (size_t)m * 1024 + c) = wv;
;             }
;         }
;         if (!last && lane == 0) ((f32x2*)((unsigned char*)p.out + OFFO_STATS))[m] = (f32x2){mu, rstd};
.LBB0_1783:
	v_add_f32_e64 v38, v58, v44
	v_add_f32_e64 v39, v59, v45
	v_add_f32_e64 v46, v70, v36
	v_add_f32_e64 v47, v71, v37
	v_add_f32_e32 v38, v38, v39
	v_add_f32_e64 v47, v46, v47
	v_add_f32_e64 v46, v46, v46
	v_add_f32_e32 v39, 0, v38
	s_waitcnt vmcnt(2)
	v_add_f32_e32 v49, v32, v33
	v_add_f32_e32 v51, v34, v35
	s_waitcnt vmcnt(1)
	v_mov_b32_e32 v48, v40
	v_mov_b32_e32 v50, v41
	v_mov_b32_e32 v46, v42
	v_mov_b32_e32 v38, v43
	v_add_f32_e64 v48, v48, v50
	v_add_f32_e64 v49, v49, v51
	v_add_f32_e64 v38, v46, v38
	v_add_f32_e64 v39, v47, v39
	v_add_u32_e32 v62, s34, v62
	v_add_f32_e64 v38, v48, v38
	v_add_f32_e64 v39, v49, v39
	v_mov_b32_e32 v78, v59
	v_add_f32_e32 v38, v38, v39
	ds_bpermute_b32 v39, v63, v38
	v_mov_b32_e32 v79, v45
	v_mov_b32_e32 v45, v58
	v_mov_b32_e32 v86, v71
	v_mov_b32_e32 v87, v37
	s_waitcnt lgkmcnt(0)
	v_add_f32_e32 v38, v38, v39
	ds_bpermute_b32 v39, v73, v38
	v_mov_b32_e32 v37, v70
	s_waitcnt lgkmcnt(0)
	v_add_f32_e32 v38, v38, v39
	ds_bpermute_b32 v39, v74, v38
	s_waitcnt lgkmcnt(0)
	v_add_f32_e32 v38, v38, v39
	ds_bpermute_b32 v39, v75, v38
	s_waitcnt lgkmcnt(0)
	v_add_f32_e32 v46, v38, v39
	ds_bpermute_b32 v47, v76, v46
	v_min_i32_e32 v38, 0x803f, v62
	v_ashrrev_i32_e32 v39, 31, v38
	v_lshlrev_b64 v[38:39], 12, v[38:39]
	v_lshl_add_u64 v[38:39], v[64:65], 0, v[38:39]
	s_waitcnt lgkmcnt(0)
	v_add_f32_e32 v80, v46, v47
	global_load_dwordx4 v[58:61], v[38:39], off
	global_load_dwordx4 v[54:57], v[38:39], off offset:1024
	global_load_dwordx4 v[50:53], v[38:39], off offset:2048
	global_load_dwordx4 v[46:49], v[38:39], off offset:3072
	ds_bpermute_b32 v81, v77, v80
	s_waitcnt lgkmcnt(0)
	v_add_f32_e32 v38, v80, v81
	v_mul_f32_e32 v38, 0x3a800000, v38
	v_add_f32_e64 v44, v44, -v38
	v_add_f32_e64 v45, v45, -v38
	v_add_f32_e64 v78, v78, -v38
	v_add_f32_e64 v79, v79, -v38
	v_mul_f32_e64 v84, v44, v44
	v_mul_f32_e64 v85, v45, v45
	v_add_f32_e64 v42, v42, -v38
	v_add_f32_e64 v43, v43, -v38
	v_mul_f32_e64 v82, v78, v78
	v_mul_f32_e64 v83, v79, v79
	v_add_f32_e64 v86, v86, -v38
	v_add_f32_e64 v87, v87, -v38
	v_add_f32_e64 v36, v36, -v38
	v_add_f32_e64 v37, v37, -v38
	v_add_f32_e64 v34, v34, -v38
	v_add_f32_e64 v35, v35, -v38
	v_add_f32_e64 v92, v32, -v38
	v_add_f32_e64 v93, v33, -v38
	v_add_f32_e64 v40, v40, -v38
	v_add_f32_e64 v41, v41, -v38
	v_add_f32_e32 v39, v84, v85
	v_add_f32_e32 v39, v82, v39
	v_mul_f32_e64 v70, v36, v36
	v_mul_f32_e64 v71, v37, v37
	v_add_f32_e32 v39, v83, v39
	v_add_f32_e32 v39, v70, v39
	v_mul_f32_e64 v88, v86, v86
	v_mul_f32_e64 v89, v87, v87
	v_add_f32_e32 v39, v71, v39
	v_add_f32_e32 v39, v88, v39
	v_mul_f32_e64 v32, v92, v92
	v_mul_f32_e64 v33, v93, v93
	v_add_f32_e32 v39, v89, v39
	v_add_f32_e32 v32, v32, v39
	v_mul_f32_e64 v90, v34, v34
	v_mul_f32_e64 v91, v35, v35
	v_add_f32_e32 v32, v33, v32
	v_add_f32_e32 v32, v90, v32
	v_mul_f32_e64 v94, v40, v40
	v_mul_f32_e64 v95, v41, v41
	v_add_f32_e32 v32, v91, v32
	v_add_f32_e32 v32, v94, v32
	v_mul_f32_e64 v80, v42, v42
	v_mul_f32_e64 v81, v43, v43
	v_add_f32_e32 v32, v95, v32
	v_add_f32_e32 v32, v80, v32
	v_add_f32_e32 v32, v81, v32
	ds_bpermute_b32 v33, v63, v32
	s_waitcnt lgkmcnt(0)
	v_add_f32_e32 v32, v32, v33
	ds_bpermute_b32 v33, v73, v32
	s_waitcnt lgkmcnt(0)
	v_add_f32_e32 v32, v32, v33
	ds_bpermute_b32 v33, v74, v32
	s_waitcnt lgkmcnt(0)
	v_add_f32_e32 v32, v32, v33
	ds_bpermute_b32 v33, v75, v32
	s_waitcnt lgkmcnt(0)
	v_add_f32_e32 v32, v32, v33
	ds_bpermute_b32 v33, v76, v32
	s_waitcnt lgkmcnt(0)
	v_add_f32_e32 v32, v32, v33
	ds_bpermute_b32 v33, v77, v32
	s_waitcnt lgkmcnt(0)
	v_add_f32_e32 v32, v32, v33
	v_fmamk_f32 v32, v32, 0x3a800000, v72
	v_rsq_f32_e32 v32, v32
	s_nop 0
	v_mul_f32_e64 v44, v44, v32
	v_mul_f32_e64 v45, v45, v32
	v_mul_f32_e64 v70, v78, v32
	v_mul_f32_e64 v71, v79, v32
	v_mul_f32_e64 v36, v36, v32
	v_mul_f32_e64 v37, v37, v32
	v_mul_f32_e64 v78, v86, v32
	v_mul_f32_e64 v79, v87, v32
	v_mul_f32_e64 v80, v92, v32
	v_mul_f32_e64 v81, v93, v32
	v_mul_f32_e64 v34, v34, v32
	v_mul_f32_e64 v35, v35, v32
	s_waitcnt vmcnt(4)
	v_fma_f32 v44, v28, v44, v24
	v_fma_f32 v45, v29, v45, v25
	v_fma_f32 v70, v30, v70, v26
	v_fma_f32 v71, v31, v71, v27
	v_fma_f32 v36, v20, v36, v12
	v_fma_f32 v37, v21, v37, v13
	v_fma_f32 v78, v22, v78, v14
	v_fma_f32 v79, v23, v79, v15
	v_fma_f32 v80, v16, v80, v8
	v_fma_f32 v81, v17, v81, v9
	v_cvt_pk_bf16_f32 v44, v44, v45
	v_cvt_pk_bf16_f32 v45, v70, v71
	v_cvt_pk_bf16_f32 v36, v36, v37
	v_cvt_pk_bf16_f32 v37, v78, v79
	v_fma_f32 v34, v18, v34, v10
	v_fma_f32 v35, v19, v35, v11
	global_store_dwordx2 v[68:69], v[44:45], off
	global_store_dwordx2 v[68:69], v[36:37], off offset:512
	v_cvt_pk_bf16_f32 v36, v80, v81
	v_cvt_pk_bf16_f32 v37, v34, v35
	global_store_dwordx2 v[68:69], v[36:37], off offset:1024
	v_mul_f32_e64 v34, v40, v32
	v_mul_f32_e64 v35, v41, v32
	v_mul_f32_e64 v36, v42, v32
	v_mul_f32_e64 v37, v43, v32
	v_fma_f32 v34, v4, v34, v0
	v_fma_f32 v35, v5, v35, v1
	v_fma_f32 v36, v6, v36, v2
	v_fma_f32 v37, v7, v37, v3
	v_cvt_pk_bf16_f32 v34, v34, v35
	v_cvt_pk_bf16_f32 v35, v36, v37
	global_store_dwordx2 v[68:69], v[34:35], off offset:1536
	s_and_saveexec_b64 s[6:7], vcc
	s_cbranch_execz .LBB0_1782
	v_mov_b32_e32 v39, v32
	global_store_dwordx2 v[66:67], v[38:39], off
	s_branch .LBB0_1782

; DI void ph_ln(const Params& p, int lnidx, bool last) {
;     ...
;     for (int m = gw; m < MT; m += nw) {
;         f32x4 v[4];
; #pragma unroll
;         for (int i = 0; i < 4; ++i) v[i] = nv[i];
;         const int mn = min(m + nw, MT - 1);
; #pragma unroll
;         for (int i = 0; i < 4; ++i) nv[i] = *(const f32x4*)(H + (size_t)mn * 1024 + i * 256 + lane * 4);
;         float s = 0.f;
; #pragma unroll
;         for (int i = 0; i < 4; ++i) s += (v[i][0] + v[i][1]) + (v[i][2] + v[i][3]);
;         for (int o = 32; o > 0; o >>= 1) s += __shfl_xor(s, o);
;         const float mu = s * (1.0f / 1024.0f);
;         float qv = 0.f;
; #pragma unroll
;         for (int i = 0; i < 4; ++i)
; #pragma unroll
;             for (int e = 0; e < 4; ++e) { const float d = v[i][e] - mu; qv += d * d; }
;         for (int o = 32; o > 0; o >>= 1) qv += __shfl_xor(qv, o);
;         const float rstd = __frsqrt_rn(qv * (1.0f / 1024.0f) + 1e-5f);
;         const int b = m / LT, pos = m - b * LT;
; #pragma unroll
;         for (int i = 0; i < 4; ++i) {
;             const int c = i * 256 + lane * 4;
;             f32x4 y;
; #pragma unroll
;             for (int e = 0; e < 4; ++e) y[e] = (v[i][e] - mu) * rstd * g[i][e] + bb[i][e];
;             if (last) {
;                 if (pos >= 16) *(f32x4*)(p.out + ((size_t)b * 8192 + (pos - 16)) * 1024 + c) = y;
.LBB0_1996:
	v_add_f32_e64 v42, v72, v44
	v_add_f32_e64 v43, v73, v45
	v_add_f32_e64 v46, v70, v40
	v_add_f32_e64 v47, v71, v41
	v_add_f32_e32 v42, v42, v43
	v_add_f32_e64 v47, v46, v47
	v_add_f32_e64 v46, v46, v46
	v_add_f32_e32 v43, 0, v42
	s_waitcnt vmcnt(2)
	v_add_f32_e32 v49, v32, v33
	v_add_f32_e32 v51, v34, v35
	s_waitcnt vmcnt(1)
	v_mov_b32_e32 v48, v36
	v_mov_b32_e32 v50, v37
	v_mov_b32_e32 v46, v38
	v_mov_b32_e32 v42, v39
	v_add_f32_e64 v48, v48, v50
	v_add_f32_e64 v49, v49, v51
	v_add_f32_e64 v42, v46, v42
	v_add_f32_e64 v43, v47, v43
	v_mov_b32_e32 v67, v62
	v_add_f32_e64 v42, v48, v42
	v_add_f32_e64 v43, v49, v43
	v_add_u32_e32 v62, s34, v67
	v_add_f32_e32 v42, v42, v43
	ds_bpermute_b32 v43, v76, v42
	s_waitcnt lgkmcnt(0)
	v_add_f32_e32 v42, v42, v43
	ds_bpermute_b32 v43, v77, v42
	s_waitcnt lgkmcnt(0)
	v_add_f32_e32 v42, v42, v43
	ds_bpermute_b32 v43, v78, v42
	s_waitcnt lgkmcnt(0)
	v_add_f32_e32 v46, v42, v43
	ds_bpermute_b32 v47, v79, v46
	v_min_i32_e32 v42, 0x803f, v62
	v_ashrrev_i32_e32 v43, 31, v42
	v_lshlrev_b64 v[42:43], 12, v[42:43]
	v_lshl_add_u64 v[42:43], v[68:69], 0, v[42:43]
	s_waitcnt lgkmcnt(0)
	v_add_f32_e32 v64, v46, v47
	global_load_dwordx4 v[58:61], v[42:43], off
	global_load_dwordx4 v[54:57], v[42:43], off offset:1024
	global_load_dwordx4 v[50:53], v[42:43], off offset:2048
	global_load_dwordx4 v[46:49], v[42:43], off offset:3072
	ds_bpermute_b32 v74, v80, v64
	v_mov_b32_e32 v42, v44
	v_mov_b32_e32 v43, v72
	v_mov_b32_e32 v44, v73
	s_waitcnt lgkmcnt(0)
	v_add_f32_e32 v64, v64, v74
	ds_bpermute_b32 v74, v81, v64
	s_waitcnt lgkmcnt(0)
	v_add_f32_e32 v64, v64, v74
	v_mul_f32_e32 v64, 0x3a800000, v64
	v_add_f32_e64 v72, v42, -v64
	v_add_f32_e64 v73, v43, -v64
	v_add_f32_e64 v74, v44, -v64
	v_add_f32_e64 v75, v45, -v64
	v_mul_f32_e64 v82, v72, v72
	v_mul_f32_e64 v83, v73, v73
	v_mov_b32_e32 v42, v40
	v_mov_b32_e32 v43, v70
	v_mov_b32_e32 v40, v71
	v_mul_f32_e64 v84, v74, v74
	v_mul_f32_e64 v85, v75, v75
	v_add_f32_e64 v44, v42, -v64
	v_add_f32_e64 v45, v43, -v64
	v_add_f32_e64 v70, v40, -v64
	v_add_f32_e64 v71, v41, -v64
	v_add_f32_e64 v40, v32, -v64
	v_add_f32_e64 v41, v33, -v64
	v_add_f32_e64 v42, v34, -v64
	v_add_f32_e64 v43, v35, -v64
	v_add_f32_e64 v32, v36, -v64
	v_add_f32_e64 v33, v37, -v64
	v_add_f32_e64 v34, v38, -v64
	v_add_f32_e64 v35, v39, -v64
	v_add_f32_e32 v64, v82, v83
	v_add_f32_e32 v64, v84, v64
	v_mul_f32_e64 v86, v44, v44
	v_mul_f32_e64 v87, v45, v45
	v_add_f32_e32 v64, v85, v64
	v_add_f32_e32 v64, v86, v64
	v_mul_f32_e64 v88, v70, v70
	v_mul_f32_e64 v89, v71, v71
	v_add_f32_e32 v64, v87, v64
	v_add_f32_e32 v64, v88, v64
	v_mul_f32_e64 v90, v40, v40
	v_mul_f32_e64 v91, v41, v41
	v_add_f32_e32 v64, v89, v64
	v_add_f32_e32 v64, v90, v64
	v_mul_f32_e64 v92, v42, v42
	v_mul_f32_e64 v93, v43, v43
	v_add_f32_e32 v64, v91, v64
	v_add_f32_e32 v64, v92, v64
	v_mul_f32_e64 v36, v32, v32
	v_mul_f32_e64 v37, v33, v33
	v_add_f32_e32 v64, v93, v64
	v_add_f32_e32 v36, v36, v64
	v_mul_f32_e64 v38, v34, v34
	v_mul_f32_e64 v39, v35, v35
	v_add_f32_e32 v36, v37, v36
	v_add_f32_e32 v36, v38, v36
	v_add_f32_e32 v36, v39, v36
	ds_bpermute_b32 v37, v76, v36
	v_mul_hi_i32 v39, v67, s5
	s_waitcnt lgkmcnt(0)
	v_add_f32_e32 v36, v36, v37
	ds_bpermute_b32 v37, v77, v36
	s_waitcnt lgkmcnt(0)
	v_add_f32_e32 v36, v36, v37
	ds_bpermute_b32 v37, v78, v36
	s_waitcnt lgkmcnt(0)
	v_add_f32_e32 v36, v36, v37
	ds_bpermute_b32 v37, v79, v36
	s_waitcnt lgkmcnt(0)
	v_add_f32_e32 v36, v36, v37
	ds_bpermute_b32 v37, v80, v36
	s_waitcnt lgkmcnt(0)
	v_add_f32_e32 v37, v36, v37
	ds_bpermute_b32 v38, v81, v37
	v_lshrrev_b32_e32 v36, 31, v39
	v_ashrrev_i32_e32 v39, 12, v39
	v_add_u32_e32 v36, v39, v36
	v_mad_i32_i24 v39, v36, s6, v67
	v_cmp_lt_i32_e32 vcc, 15, v39
	s_and_saveexec_b64 s[2:3], vcc
	s_cbranch_execz .LBB0_1995
	s_waitcnt lgkmcnt(0)
	v_add_f32_e32 v37, v37, v38
	v_fmamk_f32 v37, v37, 0x3a800000, v63
	v_rsq_f32_e32 v82, v37
	v_ashrrev_i32_e32 v37, 31, v36
	v_add_u32_e32 v64, -16, v39
	v_lshlrev_b64 v[86:87], 25, v[36:37]
	v_lshlrev_b64 v[84:85], 12, v[64:65]
	v_mul_f32_e64 v36, v72, v82
	v_mul_f32_e64 v37, v73, v82
	v_lshl_add_u64 v[72:73], s[54:55], 0, v[86:87]
	v_mul_f32_e64 v38, v74, v82
	v_mul_f32_e64 v39, v75, v82
	v_lshl_add_u64 v[72:73], v[72:73], 0, v[84:85]
	v_mov_b32_e32 v67, v65
	s_waitcnt vmcnt(4)
	v_fma_f32 v38, v30, v38, v26
	v_fma_f32 v39, v31, v39, v27
	v_fma_f32 v36, v28, v36, v24
	v_fma_f32 v37, v29, v37, v25
	v_lshl_add_u64 v[72:73], v[72:73], 0, v[66:67]
	global_store_dwordx4 v[72:73], v[36:39], off
	v_mul_f32_e64 v32, v32, v82
	v_mul_f32_e64 v33, v33, v82
	v_mul_f32_e64 v34, v34, v82
	v_mul_f32_e64 v35, v35, v82
	v_mul_f32_e64 v36, v44, v82
	v_mul_f32_e64 v37, v45, v82
	v_mul_f32_e64 v38, v70, v82
	v_mul_f32_e64 v39, v71, v82
	v_fma_f32 v36, v20, v36, v12
	v_fma_f32 v37, v21, v37, v13
	v_fma_f32 v38, v22, v38, v14
	v_fma_f32 v39, v23, v39, v15
	global_store_dwordx4 v[72:73], v[36:39], off offset:1024
	v_fma_f32 v34, v6, v34, v2
	v_fma_f32 v35, v7, v35, v3
	v_fma_f32 v32, v4, v32, v0
	v_fma_f32 v33, v5, v33, v1
	v_mul_f32_e64 v36, v40, v82
	v_mul_f32_e64 v37, v41, v82
	v_mul_f32_e64 v38, v42, v82
	v_mul_f32_e64 v39, v43, v82
	v_fma_f32 v36, v16, v36, v8
	v_fma_f32 v37, v17, v37, v9
	v_fma_f32 v38, v18, v38, v10
	v_fma_f32 v39, v19, v39, v11
	global_store_dwordx4 v[72:73], v[36:39], off offset:2048
	global_store_dwordx4 v[72:73], v[32:35], off offset:3072
	s_branch .LBB0_1995
